# attention C epilogue de-serialised: 16 subln gain loads issued together up front, one vmcnt wait instead of a load-wait-store ladder
# speedup vs baseline: 1.0139x; 1.0010x over previous
.LBB0_761:
	s_andn2_b64 vcc, exec, s[34:35]
	s_waitcnt lgkmcnt(0)
	s_barrier
	s_cbranch_vccnz .LBB0_738
	global_load_dwordx4 v[144:147], v[200:201], off
	global_load_dwordx4 v[148:151], v[200:201], off offset:32
	global_load_dwordx4 v[152:155], v[200:201], off offset:64
	global_load_dwordx4 v[156:159], v[200:201], off offset:96
	global_load_dwordx4 v[160:163], v[200:201], off offset:128
	global_load_dwordx4 v[164:167], v[200:201], off offset:160
	global_load_dwordx4 v[168:171], v[200:201], off offset:192
	global_load_dwordx4 v[172:175], v[200:201], off offset:224
	global_load_dwordx4 v[176:179], v[200:201], off offset:256
	global_load_dwordx4 v[180:183], v[200:201], off offset:288
	global_load_dwordx4 v[184:187], v[200:201], off offset:320
	global_load_dwordx4 v[188:191], v[200:201], off offset:352
	global_load_dwordx4 v[224:227], v[200:201], off offset:384
	global_load_dwordx4 v[228:231], v[200:201], off offset:416
	global_load_dwordx4 v[244:247], v[200:201], off offset:448
	global_load_dwordx4 v[248:251], v[200:201], off offset:480
	v_add_u32_e32 v64, s52, v237
	ds_read_b128 v[86:89], v64
	ds_read_b128 v[90:93], v64 offset:1024
	ds_read_b128 v[94:97], v64 offset:2048
	ds_read_b128 v[98:101], v64 offset:3072
	ds_read_b128 v[102:105], v64 offset:4096
	ds_read_b128 v[106:109], v64 offset:5120
	ds_read_b128 v[110:113], v64 offset:6144
	ds_read_b128 v[114:117], v64 offset:7168
	ds_read_b128 v[118:121], v64 offset:8192
	ds_read_b128 v[122:125], v64 offset:9216
	ds_read_b128 v[126:129], v64 offset:10240
	ds_read_b128 v[130:133], v64 offset:11264
	ds_read_b128 v[134:137], v64 offset:12288
	ds_read_b128 v[138:141], v64 offset:13312
	ds_read_b128 v[72:75], v64 offset:14336
	ds_read_b128 v[76:79], v64 offset:15360
	s_waitcnt lgkmcnt(14)
	v_pk_mul_f32 v[84:85], v[194:195], v[92:93]
	v_or_b32_e32 v64, s8, v236
	v_pk_fma_f32 v[54:55], v[54:55], v[80:81], v[84:85] op_sel_hi:[1,0,1] neg_lo:[0,0,1] neg_hi:[0,0,1]
	v_pk_mul_f32 v[84:85], v[194:195], v[90:91]
	v_lshl_or_b32 v64, v64, 9, s40
	v_pk_fma_f32 v[52:53], v[52:53], v[80:81], v[84:85] op_sel_hi:[1,0,1] neg_lo:[0,0,1] neg_hi:[0,0,1]
	v_pk_mul_f32 v[84:85], v[194:195], v[88:89]
	v_mov_b32_e32 v65, s41
	v_pk_fma_f32 v[84:85], v[50:51], v[80:81], v[84:85] op_sel_hi:[1,0,1] neg_lo:[0,0,1] neg_hi:[0,0,1]
	v_pk_mul_f32 v[50:51], v[194:195], v[86:87]
	v_lshl_add_u64 v[82:83], v[64:65], 1, s[12:13]
	v_pk_fma_f32 v[86:87], v[48:49], v[80:81], v[50:51] op_sel_hi:[1,0,1] neg_lo:[0,0,1] neg_hi:[0,0,1]
	v_mul_f32_e32 v50, v85, v85
	v_mul_f32_e32 v48, v87, v87
	v_pk_fma_f32 v[48:49], v[86:87], v[86:87], v[48:49] op_sel_hi:[1,1,0]
	v_pk_fma_f32 v[48:49], v[84:85], v[84:85], v[48:49]
	s_lshl_b32 s8, s57, 1
	v_pk_add_f32 v[48:49], v[50:51], v[48:49] op_sel_hi:[0,1]
	v_pk_fma_f32 v[48:49], v[52:53], v[52:53], v[48:49]
	v_mul_f32_e32 v50, v53, v53
	v_pk_add_f32 v[48:49], v[50:51], v[48:49] op_sel_hi:[0,1]
	v_pk_fma_f32 v[48:49], v[54:55], v[54:55], v[48:49]
	v_mul_f32_e32 v50, v55, v55
	v_pk_add_f32 v[88:89], v[50:51], v[48:49] op_sel_hi:[0,1]
	s_waitcnt lgkmcnt(12)
	v_pk_mul_f32 v[50:51], v[194:195], v[98:99]
	v_pk_mul_f32 v[48:49], v[194:195], v[100:101]
	v_pk_fma_f32 v[50:51], v[60:61], v[80:81], v[50:51] op_sel_hi:[1,0,1] neg_lo:[0,0,1] neg_hi:[0,0,1]
	v_pk_mul_f32 v[60:61], v[194:195], v[96:97]
	v_pk_fma_f32 v[48:49], v[62:63], v[80:81], v[48:49] op_sel_hi:[1,0,1] neg_lo:[0,0,1] neg_hi:[0,0,1]
	v_pk_fma_f32 v[58:59], v[58:59], v[80:81], v[60:61] op_sel_hi:[1,0,1] neg_lo:[0,0,1] neg_hi:[0,0,1]
	v_pk_mul_f32 v[60:61], v[194:195], v[94:95]
	v_mov_b32_e32 v215, v193
	v_pk_fma_f32 v[62:63], v[56:57], v[80:81], v[60:61] op_sel_hi:[1,0,1] neg_lo:[0,0,1] neg_hi:[0,0,1]
	s_nop 0
	v_pk_fma_f32 v[56:57], v[62:63], v[62:63], v[88:89]
	v_mul_f32_e32 v60, v63, v63
	v_pk_add_f32 v[56:57], v[60:61], v[56:57] op_sel_hi:[0,1]
	v_pk_fma_f32 v[56:57], v[58:59], v[58:59], v[56:57]
	v_mul_f32_e32 v60, v59, v59
	v_pk_add_f32 v[56:57], v[60:61], v[56:57] op_sel_hi:[0,1]
	v_pk_fma_f32 v[56:57], v[50:51], v[50:51], v[56:57]
	v_mul_f32_e32 v60, v51, v51
	v_pk_add_f32 v[56:57], v[60:61], v[56:57] op_sel_hi:[0,1]
	v_pk_fma_f32 v[56:57], v[48:49], v[48:49], v[56:57]
	v_mul_f32_e32 v60, v49, v49
	v_pk_add_f32 v[88:89], v[60:61], v[56:57] op_sel_hi:[0,1]
	s_waitcnt lgkmcnt(10)
	v_pk_mul_f32 v[56:57], v[194:195], v[108:109]
	s_nop 0
	v_pk_fma_f32 v[38:39], v[38:39], v[80:81], v[56:57] op_sel_hi:[1,0,1] neg_lo:[0,0,1] neg_hi:[0,0,1]
	v_pk_mul_f32 v[56:57], v[194:195], v[106:107]
	s_nop 0
	v_pk_fma_f32 v[36:37], v[36:37], v[80:81], v[56:57] op_sel_hi:[1,0,1] neg_lo:[0,0,1] neg_hi:[0,0,1]
	v_pk_mul_f32 v[56:57], v[194:195], v[104:105]
	s_nop 0
	v_pk_fma_f32 v[56:57], v[34:35], v[80:81], v[56:57] op_sel_hi:[1,0,1] neg_lo:[0,0,1] neg_hi:[0,0,1]
	v_pk_mul_f32 v[34:35], v[194:195], v[102:103]
	s_nop 0
	v_pk_fma_f32 v[60:61], v[32:33], v[80:81], v[34:35] op_sel_hi:[1,0,1] neg_lo:[0,0,1] neg_hi:[0,0,1]
	s_nop 0
	v_pk_fma_f32 v[32:33], v[60:61], v[60:61], v[88:89]
	v_mul_f32_e32 v34, v61, v61
	v_pk_add_f32 v[32:33], v[34:35], v[32:33] op_sel_hi:[0,1]
	v_pk_fma_f32 v[32:33], v[56:57], v[56:57], v[32:33]
	v_mul_f32_e32 v34, v57, v57
	v_pk_add_f32 v[32:33], v[34:35], v[32:33] op_sel_hi:[0,1]
	v_pk_fma_f32 v[32:33], v[36:37], v[36:37], v[32:33]
	v_mul_f32_e32 v34, v37, v37
	v_pk_add_f32 v[32:33], v[34:35], v[32:33] op_sel_hi:[0,1]
	v_pk_fma_f32 v[32:33], v[38:39], v[38:39], v[32:33]
	v_mul_f32_e32 v34, v39, v39
	v_pk_add_f32 v[88:89], v[34:35], v[32:33] op_sel_hi:[0,1]
	s_waitcnt lgkmcnt(8)
	v_pk_mul_f32 v[34:35], v[194:195], v[114:115]
	v_pk_mul_f32 v[32:33], v[194:195], v[116:117]
	v_pk_fma_f32 v[34:35], v[44:45], v[80:81], v[34:35] op_sel_hi:[1,0,1] neg_lo:[0,0,1] neg_hi:[0,0,1]
	v_pk_mul_f32 v[44:45], v[194:195], v[112:113]
	v_pk_fma_f32 v[32:33], v[46:47], v[80:81], v[32:33] op_sel_hi:[1,0,1] neg_lo:[0,0,1] neg_hi:[0,0,1]
	v_pk_fma_f32 v[42:43], v[42:43], v[80:81], v[44:45] op_sel_hi:[1,0,1] neg_lo:[0,0,1] neg_hi:[0,0,1]
	v_pk_mul_f32 v[44:45], v[194:195], v[110:111]
	s_nop 0
	v_pk_fma_f32 v[46:47], v[40:41], v[80:81], v[44:45] op_sel_hi:[1,0,1] neg_lo:[0,0,1] neg_hi:[0,0,1]
	s_nop 0
	v_pk_fma_f32 v[40:41], v[46:47], v[46:47], v[88:89]
	v_mul_f32_e32 v44, v47, v47
	v_pk_add_f32 v[40:41], v[44:45], v[40:41] op_sel_hi:[0,1]
	v_pk_fma_f32 v[40:41], v[42:43], v[42:43], v[40:41]
	v_mul_f32_e32 v44, v43, v43
	v_pk_add_f32 v[40:41], v[44:45], v[40:41] op_sel_hi:[0,1]
	v_pk_fma_f32 v[40:41], v[34:35], v[34:35], v[40:41]
	v_mul_f32_e32 v44, v35, v35
	v_pk_add_f32 v[40:41], v[44:45], v[40:41] op_sel_hi:[0,1]
	v_pk_fma_f32 v[40:41], v[32:33], v[32:33], v[40:41]
	v_mul_f32_e32 v44, v33, v33
	v_pk_add_f32 v[88:89], v[44:45], v[40:41] op_sel_hi:[0,1]
	s_waitcnt lgkmcnt(6)
	v_pk_mul_f32 v[40:41], v[194:195], v[124:125]
	s_nop 0
	v_pk_fma_f32 v[22:23], v[22:23], v[80:81], v[40:41] op_sel_hi:[1,0,1] neg_lo:[0,0,1] neg_hi:[0,0,1]
	v_pk_mul_f32 v[40:41], v[194:195], v[122:123]
	s_nop 0
	v_pk_fma_f32 v[20:21], v[20:21], v[80:81], v[40:41] op_sel_hi:[1,0,1] neg_lo:[0,0,1] neg_hi:[0,0,1]
	v_pk_mul_f32 v[40:41], v[194:195], v[120:121]
	s_nop 0
	v_pk_fma_f32 v[40:41], v[18:19], v[80:81], v[40:41] op_sel_hi:[1,0,1] neg_lo:[0,0,1] neg_hi:[0,0,1]
	v_pk_mul_f32 v[18:19], v[194:195], v[118:119]
	s_nop 0
	v_pk_fma_f32 v[44:45], v[16:17], v[80:81], v[18:19] op_sel_hi:[1,0,1] neg_lo:[0,0,1] neg_hi:[0,0,1]
	s_nop 0
	v_pk_fma_f32 v[16:17], v[44:45], v[44:45], v[88:89]
	v_mul_f32_e32 v18, v45, v45
	v_pk_add_f32 v[16:17], v[18:19], v[16:17] op_sel_hi:[0,1]
	v_pk_fma_f32 v[16:17], v[40:41], v[40:41], v[16:17]
	v_mul_f32_e32 v18, v41, v41
	v_pk_add_f32 v[16:17], v[18:19], v[16:17] op_sel_hi:[0,1]
	v_pk_fma_f32 v[16:17], v[20:21], v[20:21], v[16:17]
	v_mul_f32_e32 v18, v21, v21
	v_pk_add_f32 v[16:17], v[18:19], v[16:17] op_sel_hi:[0,1]
	v_pk_fma_f32 v[16:17], v[22:23], v[22:23], v[16:17]
	v_mul_f32_e32 v18, v23, v23
	v_pk_add_f32 v[88:89], v[18:19], v[16:17] op_sel_hi:[0,1]
	s_waitcnt lgkmcnt(4)
	v_pk_mul_f32 v[18:19], v[194:195], v[130:131]
	v_pk_mul_f32 v[16:17], v[194:195], v[132:133]
	v_pk_fma_f32 v[18:19], v[28:29], v[80:81], v[18:19] op_sel_hi:[1,0,1] neg_lo:[0,0,1] neg_hi:[0,0,1]
	v_pk_mul_f32 v[28:29], v[194:195], v[128:129]
	v_pk_fma_f32 v[16:17], v[30:31], v[80:81], v[16:17] op_sel_hi:[1,0,1] neg_lo:[0,0,1] neg_hi:[0,0,1]
	v_pk_fma_f32 v[26:27], v[26:27], v[80:81], v[28:29] op_sel_hi:[1,0,1] neg_lo:[0,0,1] neg_hi:[0,0,1]
	v_pk_mul_f32 v[28:29], v[194:195], v[126:127]
	s_nop 0
	v_pk_fma_f32 v[30:31], v[24:25], v[80:81], v[28:29] op_sel_hi:[1,0,1] neg_lo:[0,0,1] neg_hi:[0,0,1]
	s_nop 0
	v_pk_fma_f32 v[24:25], v[30:31], v[30:31], v[88:89]
	v_mul_f32_e32 v28, v31, v31
	v_pk_add_f32 v[24:25], v[28:29], v[24:25] op_sel_hi:[0,1]
	v_pk_fma_f32 v[24:25], v[26:27], v[26:27], v[24:25]
	v_mul_f32_e32 v28, v27, v27
	v_pk_add_f32 v[24:25], v[28:29], v[24:25] op_sel_hi:[0,1]
	v_pk_fma_f32 v[24:25], v[18:19], v[18:19], v[24:25]
	v_mul_f32_e32 v28, v19, v19
	v_pk_add_f32 v[24:25], v[28:29], v[24:25] op_sel_hi:[0,1]
	v_pk_fma_f32 v[24:25], v[16:17], v[16:17], v[24:25]
	v_mul_f32_e32 v28, v17, v17
	v_pk_add_f32 v[88:89], v[28:29], v[24:25] op_sel_hi:[0,1]
	s_waitcnt lgkmcnt(2)
	v_pk_mul_f32 v[24:25], v[194:195], v[140:141]
	s_nop 0
	v_pk_fma_f32 v[6:7], v[6:7], v[80:81], v[24:25] op_sel_hi:[1,0,1] neg_lo:[0,0,1] neg_hi:[0,0,1]
	v_pk_mul_f32 v[24:25], v[194:195], v[138:139]
	s_nop 0
	v_pk_fma_f32 v[4:5], v[4:5], v[80:81], v[24:25] op_sel_hi:[1,0,1] neg_lo:[0,0,1] neg_hi:[0,0,1]
	v_pk_mul_f32 v[24:25], v[194:195], v[136:137]
	s_nop 0
	v_pk_fma_f32 v[24:25], v[2:3], v[80:81], v[24:25] op_sel_hi:[1,0,1] neg_lo:[0,0,1] neg_hi:[0,0,1]
	v_pk_mul_f32 v[2:3], v[194:195], v[134:135]
	s_nop 0
	v_pk_fma_f32 v[28:29], v[0:1], v[80:81], v[2:3] op_sel_hi:[1,0,1] neg_lo:[0,0,1] neg_hi:[0,0,1]
	s_nop 0
	v_pk_fma_f32 v[0:1], v[28:29], v[28:29], v[88:89]
	v_mul_f32_e32 v2, v29, v29
	v_pk_add_f32 v[0:1], v[2:3], v[0:1] op_sel_hi:[0,1]
	v_pk_fma_f32 v[0:1], v[24:25], v[24:25], v[0:1]
	v_mul_f32_e32 v2, v25, v25
	v_pk_add_f32 v[0:1], v[2:3], v[0:1] op_sel_hi:[0,1]
	v_pk_fma_f32 v[0:1], v[4:5], v[4:5], v[0:1]
	v_mul_f32_e32 v2, v5, v5
	v_pk_add_f32 v[0:1], v[2:3], v[0:1] op_sel_hi:[0,1]
	v_pk_fma_f32 v[0:1], v[6:7], v[6:7], v[0:1]
	v_mul_f32_e32 v2, v7, v7
	v_pk_add_f32 v[88:89], v[2:3], v[0:1] op_sel_hi:[0,1]
	s_waitcnt lgkmcnt(0)
	v_pk_mul_f32 v[2:3], v[194:195], v[76:77]
	v_pk_mul_f32 v[0:1], v[194:195], v[78:79]
	v_pk_fma_f32 v[2:3], v[12:13], v[80:81], v[2:3] op_sel_hi:[1,0,1] neg_lo:[0,0,1] neg_hi:[0,0,1]
	v_pk_mul_f32 v[12:13], v[194:195], v[74:75]
	v_pk_fma_f32 v[0:1], v[14:15], v[80:81], v[0:1] op_sel_hi:[1,0,1] neg_lo:[0,0,1] neg_hi:[0,0,1]
	v_pk_fma_f32 v[10:11], v[10:11], v[80:81], v[12:13] op_sel_hi:[1,0,1] neg_lo:[0,0,1] neg_hi:[0,0,1]
	v_pk_mul_f32 v[12:13], v[194:195], v[72:73]
	s_nop 0
	v_pk_fma_f32 v[8:9], v[8:9], v[80:81], v[12:13] op_sel_hi:[1,0,1] neg_lo:[0,0,1] neg_hi:[0,0,1]
	s_nop 0
	v_pk_fma_f32 v[12:13], v[8:9], v[8:9], v[88:89]
	v_mul_f32_e32 v14, v9, v9
	v_pk_add_f32 v[12:13], v[14:15], v[12:13] op_sel_hi:[0,1]
	v_pk_fma_f32 v[12:13], v[10:11], v[10:11], v[12:13]
	v_mul_f32_e32 v14, v11, v11
	v_pk_add_f32 v[12:13], v[14:15], v[12:13] op_sel_hi:[0,1]
	v_pk_fma_f32 v[12:13], v[2:3], v[2:3], v[12:13]
	v_mul_f32_e32 v14, v3, v3
	v_pk_add_f32 v[12:13], v[14:15], v[12:13] op_sel_hi:[0,1]
	v_pk_fma_f32 v[12:13], v[0:1], v[0:1], v[12:13]
	v_mul_f32_e32 v14, v1, v1
	v_pk_add_f32 v[12:13], v[14:15], v[12:13] op_sel_hi:[0,1]
	v_mov_b32_e32 v13, v12
	s_nop 1
	v_permlane32_swap_b32_e32 v12, v13
	v_add_f32_e32 v12, v12, v13
	v_fmamk_f32 v12, v12, 0x3c000000, v205
	v_mul_f32_e32 v13, 0x4b800000, v12
	v_cmp_gt_f32_e32 vcc, s37, v12
	s_nop 1
	v_cndmask_b32_e32 v12, v12, v13, vcc
	v_rsq_f32_e32 v14, v12
	v_lshl_add_u64 v[12:13], v[82:83], 0, s[8:9]
	v_lshl_add_u64 v[12:13], v[12:13], 0, v[214:215]
	v_mul_f32_e32 v15, 0x45800000, v14
	v_cndmask_b32_e32 v14, v14, v15, vcc
	v_mul_f32_e32 v14, 0x3f4ccccd, v14
	v_pk_mul_f32 v[72:73], v[86:87], v[14:15] op_sel_hi:[1,0]
	v_pk_mul_f32 v[52:53], v[52:53], v[14:15] op_sel_hi:[1,0]
	s_waitcnt vmcnt(0)
	v_pk_mul_f32 v[68:69], v[144:145], v[72:73]
	v_pk_mul_f32 v[72:73], v[84:85], v[14:15] op_sel_hi:[1,0]
	v_pk_mul_f32 v[52:53], v[148:149], v[52:53]
	v_pk_mul_f32 v[70:71], v[146:147], v[72:73]
	v_cvt_pk_bf16_f32 v68, v68, v69
	v_cvt_pk_bf16_f32 v69, v70, v71
	v_cvt_pk_bf16_f32 v70, v52, v53
	v_pk_mul_f32 v[52:53], v[54:55], v[14:15] op_sel_hi:[1,0]
	s_nop 0
	v_permlane32_swap_b32_e32 v68, v70
	v_pk_mul_f32 v[52:53], v[150:151], v[52:53]
	v_pk_mul_f32 v[62:63], v[62:63], v[14:15] op_sel_hi:[1,0]
	v_cvt_pk_bf16_f32 v71, v52, v53
	s_nop 1
	v_permlane32_swap_b32_e32 v69, v71
	global_store_dwordx4 v[12:13], v[68:71], off
	v_pk_mul_f32 v[58:59], v[58:59], v[14:15] op_sel_hi:[1,0]
	v_pk_mul_f32 v[50:51], v[50:51], v[14:15] op_sel_hi:[1,0]
	v_pk_mul_f32 v[48:49], v[48:49], v[14:15] op_sel_hi:[1,0]
	v_pk_mul_f32 v[56:57], v[56:57], v[14:15] op_sel_hi:[1,0]
	v_pk_mul_f32 v[36:37], v[36:37], v[14:15] op_sel_hi:[1,0]
	v_pk_mul_f32 v[38:39], v[38:39], v[14:15] op_sel_hi:[1,0]
	v_pk_mul_f32 v[46:47], v[46:47], v[14:15] op_sel_hi:[1,0]
	v_pk_mul_f32 v[42:43], v[42:43], v[14:15] op_sel_hi:[1,0]
	v_pk_mul_f32 v[34:35], v[34:35], v[14:15] op_sel_hi:[1,0]
	v_pk_mul_f32 v[32:33], v[32:33], v[14:15] op_sel_hi:[1,0]
	v_pk_mul_f32 v[40:41], v[40:41], v[14:15] op_sel_hi:[1,0]
	v_pk_mul_f32 v[20:21], v[20:21], v[14:15] op_sel_hi:[1,0]
	v_pk_mul_f32 v[22:23], v[22:23], v[14:15] op_sel_hi:[1,0]
	v_pk_mul_f32 v[30:31], v[30:31], v[14:15] op_sel_hi:[1,0]
	v_pk_mul_f32 v[26:27], v[26:27], v[14:15] op_sel_hi:[1,0]
	v_pk_mul_f32 v[18:19], v[18:19], v[14:15] op_sel_hi:[1,0]
	v_pk_mul_f32 v[16:17], v[16:17], v[14:15] op_sel_hi:[1,0]
	v_pk_mul_f32 v[24:25], v[24:25], v[14:15] op_sel_hi:[1,0]
	v_pk_mul_f32 v[4:5], v[4:5], v[14:15] op_sel_hi:[1,0]
	v_pk_mul_f32 v[6:7], v[6:7], v[14:15] op_sel_hi:[1,0]
	v_pk_mul_f32 v[8:9], v[8:9], v[14:15] op_sel_hi:[1,0]
	v_pk_mul_f32 v[10:11], v[10:11], v[14:15] op_sel_hi:[1,0]
	v_pk_mul_f32 v[2:3], v[2:3], v[14:15] op_sel_hi:[1,0]
	v_pk_mul_f32 v[0:1], v[0:1], v[14:15] op_sel_hi:[1,0]
	v_pk_mul_f32 v[52:53], v[152:153], v[62:63]
	v_pk_mul_f32 v[54:55], v[154:155], v[58:59]
	v_pk_mul_f32 v[50:51], v[156:157], v[50:51]
	v_pk_mul_f32 v[48:49], v[158:159], v[48:49]
	v_cvt_pk_bf16_f32 v52, v52, v53
	v_cvt_pk_bf16_f32 v53, v54, v55
	v_cvt_pk_bf16_f32 v54, v50, v51
	v_cvt_pk_bf16_f32 v55, v48, v49
	s_nop 0
	v_permlane32_swap_b32_e32 v52, v54
	v_permlane32_swap_b32_e32 v53, v55
	global_store_dwordx4 v[12:13], v[52:55], off offset:32
	s_nop 0
	v_pk_mul_f32 v[58:59], v[60:61], v[14:15] op_sel_hi:[1,0]
	v_pk_mul_f32 v[50:51], v[162:163], v[56:57]
	v_pk_mul_f32 v[48:49], v[160:161], v[58:59]
	v_pk_mul_f32 v[52:53], v[36:37], v[164:165]
	v_pk_mul_f32 v[54:55], v[38:39], v[166:167]
	v_cvt_pk_bf16_f32 v36, v48, v49
	v_cvt_pk_bf16_f32 v37, v50, v51
	v_cvt_pk_bf16_f32 v38, v52, v53
	v_cvt_pk_bf16_f32 v39, v54, v55
	s_nop 0
	v_permlane32_swap_b32_e32 v36, v38
	v_permlane32_swap_b32_e32 v37, v39
	global_store_dwordx4 v[12:13], v[36:39], off offset:64
	s_nop 1
	s_nop 0
	v_pk_mul_f32 v[36:37], v[46:47], v[168:169]
	v_pk_mul_f32 v[38:39], v[42:43], v[170:171]
	v_pk_mul_f32 v[34:35], v[34:35], v[172:173]
	v_pk_mul_f32 v[42:43], v[32:33], v[174:175]
	v_cvt_pk_bf16_f32 v32, v36, v37
	v_cvt_pk_bf16_f32 v33, v38, v39
	v_cvt_pk_bf16_f32 v34, v34, v35
	v_cvt_pk_bf16_f32 v35, v42, v43
	s_nop 0
	v_permlane32_swap_b32_e32 v32, v34
	v_permlane32_swap_b32_e32 v33, v35
	global_store_dwordx4 v[12:13], v[32:35], off offset:96
	s_nop 0
	v_pk_mul_f32 v[42:43], v[44:45], v[14:15] op_sel_hi:[1,0]
	v_pk_mul_f32 v[34:35], v[40:41], v[178:179]
	v_pk_mul_f32 v[32:33], v[42:43], v[176:177]
	v_pk_mul_f32 v[36:37], v[20:21], v[180:181]
	v_pk_mul_f32 v[38:39], v[22:23], v[182:183]
	v_cvt_pk_bf16_f32 v20, v32, v33
	v_cvt_pk_bf16_f32 v21, v34, v35
	v_cvt_pk_bf16_f32 v22, v36, v37
	v_cvt_pk_bf16_f32 v23, v38, v39
	s_nop 0
	v_permlane32_swap_b32_e32 v20, v22
	v_permlane32_swap_b32_e32 v21, v23
	global_store_dwordx4 v[12:13], v[20:23], off offset:128
	s_nop 1
	s_nop 0
	v_pk_mul_f32 v[20:21], v[30:31], v[184:185]
	v_pk_mul_f32 v[22:23], v[26:27], v[186:187]
	v_pk_mul_f32 v[18:19], v[18:19], v[188:189]
	v_pk_mul_f32 v[26:27], v[16:17], v[190:191]
	v_cvt_pk_bf16_f32 v16, v20, v21
	v_cvt_pk_bf16_f32 v17, v22, v23
	v_cvt_pk_bf16_f32 v18, v18, v19
	v_cvt_pk_bf16_f32 v19, v26, v27
	s_nop 0
	v_permlane32_swap_b32_e32 v16, v18
	v_permlane32_swap_b32_e32 v17, v19
	global_store_dwordx4 v[12:13], v[16:19], off offset:160
	s_nop 0
	v_pk_mul_f32 v[26:27], v[28:29], v[14:15] op_sel_hi:[1,0]
	v_pk_mul_f32 v[18:19], v[24:25], v[226:227]
	v_pk_mul_f32 v[16:17], v[26:27], v[224:225]
	v_pk_mul_f32 v[20:21], v[4:5], v[228:229]
	v_pk_mul_f32 v[22:23], v[6:7], v[230:231]
	v_cvt_pk_bf16_f32 v4, v16, v17
	v_cvt_pk_bf16_f32 v5, v18, v19
	v_cvt_pk_bf16_f32 v6, v20, v21
	v_cvt_pk_bf16_f32 v7, v22, v23
	s_nop 0
	v_permlane32_swap_b32_e32 v4, v6
	v_permlane32_swap_b32_e32 v5, v7
	global_store_dwordx4 v[12:13], v[4:7], off offset:192
	s_nop 1
	s_nop 0
	v_pk_mul_f32 v[4:5], v[8:9], v[244:245]
	v_pk_mul_f32 v[6:7], v[10:11], v[246:247]
	v_pk_mul_f32 v[2:3], v[2:3], v[248:249]
	v_pk_mul_f32 v[8:9], v[0:1], v[250:251]
	v_cvt_pk_bf16_f32 v0, v4, v5
	v_cvt_pk_bf16_f32 v1, v6, v7
	v_cvt_pk_bf16_f32 v2, v2, v3
	v_cvt_pk_bf16_f32 v3, v8, v9
	s_nop 0
	v_permlane32_swap_b32_e32 v0, v2
	v_permlane32_swap_b32_e32 v1, v3
	global_store_dwordx4 v[12:13], v[0:3], off offset:224
	s_branch .LBB0_738

.LBB0_2821:
	s_andn2_b64 vcc, exec, s[34:35]
	s_waitcnt lgkmcnt(0)
	s_barrier
	s_cbranch_vccnz .LBB0_2798
	global_load_dwordx4 v[144:147], v[200:201], off offset:512
	global_load_dwordx4 v[148:151], v[200:201], off offset:544
	global_load_dwordx4 v[152:155], v[200:201], off offset:576
	global_load_dwordx4 v[156:159], v[200:201], off offset:608
	global_load_dwordx4 v[160:163], v[200:201], off offset:640
	global_load_dwordx4 v[164:167], v[200:201], off offset:672
	global_load_dwordx4 v[168:171], v[200:201], off offset:704
	global_load_dwordx4 v[172:175], v[200:201], off offset:736
	global_load_dwordx4 v[176:179], v[200:201], off offset:768
	global_load_dwordx4 v[180:183], v[200:201], off offset:800
	global_load_dwordx4 v[184:187], v[200:201], off offset:832
	global_load_dwordx4 v[188:191], v[200:201], off offset:864
	global_load_dwordx4 v[224:227], v[200:201], off offset:896
	global_load_dwordx4 v[228:231], v[200:201], off offset:928
	global_load_dwordx4 v[244:247], v[200:201], off offset:960
	global_load_dwordx4 v[248:251], v[200:201], off offset:992
	v_add_u32_e32 v64, s52, v237
	ds_read_b128 v[86:89], v64
	ds_read_b128 v[90:93], v64 offset:1024
	ds_read_b128 v[94:97], v64 offset:2048
	ds_read_b128 v[98:101], v64 offset:3072
	ds_read_b128 v[102:105], v64 offset:4096
	ds_read_b128 v[106:109], v64 offset:5120
	ds_read_b128 v[110:113], v64 offset:6144
	ds_read_b128 v[114:117], v64 offset:7168
	ds_read_b128 v[118:121], v64 offset:8192
	ds_read_b128 v[122:125], v64 offset:9216
	ds_read_b128 v[126:129], v64 offset:10240
	ds_read_b128 v[130:133], v64 offset:11264
	ds_read_b128 v[134:137], v64 offset:12288
	ds_read_b128 v[138:141], v64 offset:13312
	ds_read_b128 v[72:75], v64 offset:14336
	ds_read_b128 v[76:79], v64 offset:15360
	s_waitcnt lgkmcnt(14)
	v_pk_mul_f32 v[84:85], v[194:195], v[92:93]
	v_or_b32_e32 v64, s8, v236
	v_pk_fma_f32 v[54:55], v[54:55], v[80:81], v[84:85] op_sel_hi:[1,0,1] neg_lo:[0,0,1] neg_hi:[0,0,1]
	v_pk_mul_f32 v[84:85], v[194:195], v[90:91]
	v_lshl_or_b32 v64, v64, 9, s38
	v_pk_fma_f32 v[52:53], v[52:53], v[80:81], v[84:85] op_sel_hi:[1,0,1] neg_lo:[0,0,1] neg_hi:[0,0,1]
	v_pk_mul_f32 v[84:85], v[194:195], v[88:89]
	v_mov_b32_e32 v65, s39
	v_pk_fma_f32 v[84:85], v[50:51], v[80:81], v[84:85] op_sel_hi:[1,0,1] neg_lo:[0,0,1] neg_hi:[0,0,1]
	v_pk_mul_f32 v[50:51], v[194:195], v[86:87]
	v_lshl_add_u64 v[82:83], v[64:65], 1, s[12:13]
	v_pk_fma_f32 v[86:87], v[48:49], v[80:81], v[50:51] op_sel_hi:[1,0,1] neg_lo:[0,0,1] neg_hi:[0,0,1]
	v_mul_f32_e32 v50, v85, v85
	v_mul_f32_e32 v48, v87, v87
	v_pk_fma_f32 v[48:49], v[86:87], v[86:87], v[48:49] op_sel_hi:[1,1,0]
	v_pk_fma_f32 v[48:49], v[84:85], v[84:85], v[48:49]
	s_lshl_b32 s8, s57, 1
	v_pk_add_f32 v[48:49], v[50:51], v[48:49] op_sel_hi:[0,1]
	v_pk_fma_f32 v[48:49], v[52:53], v[52:53], v[48:49]
	v_mul_f32_e32 v50, v53, v53
	v_pk_add_f32 v[48:49], v[50:51], v[48:49] op_sel_hi:[0,1]
	v_pk_fma_f32 v[48:49], v[54:55], v[54:55], v[48:49]
	v_mul_f32_e32 v50, v55, v55
	v_pk_add_f32 v[88:89], v[50:51], v[48:49] op_sel_hi:[0,1]
	s_waitcnt lgkmcnt(12)
	v_pk_mul_f32 v[50:51], v[194:195], v[98:99]
	v_pk_mul_f32 v[48:49], v[194:195], v[100:101]
	v_pk_fma_f32 v[50:51], v[60:61], v[80:81], v[50:51] op_sel_hi:[1,0,1] neg_lo:[0,0,1] neg_hi:[0,0,1]
	v_pk_mul_f32 v[60:61], v[194:195], v[96:97]
	v_pk_fma_f32 v[48:49], v[62:63], v[80:81], v[48:49] op_sel_hi:[1,0,1] neg_lo:[0,0,1] neg_hi:[0,0,1]
	v_pk_fma_f32 v[58:59], v[58:59], v[80:81], v[60:61] op_sel_hi:[1,0,1] neg_lo:[0,0,1] neg_hi:[0,0,1]
	v_pk_mul_f32 v[60:61], v[194:195], v[94:95]
	v_mov_b32_e32 v215, v193
	v_pk_fma_f32 v[62:63], v[56:57], v[80:81], v[60:61] op_sel_hi:[1,0,1] neg_lo:[0,0,1] neg_hi:[0,0,1]
	s_nop 0
	v_pk_fma_f32 v[56:57], v[62:63], v[62:63], v[88:89]
	v_mul_f32_e32 v60, v63, v63
	v_pk_add_f32 v[56:57], v[60:61], v[56:57] op_sel_hi:[0,1]
	v_pk_fma_f32 v[56:57], v[58:59], v[58:59], v[56:57]
	v_mul_f32_e32 v60, v59, v59
	v_pk_add_f32 v[56:57], v[60:61], v[56:57] op_sel_hi:[0,1]
	v_pk_fma_f32 v[56:57], v[50:51], v[50:51], v[56:57]
	v_mul_f32_e32 v60, v51, v51
	v_pk_add_f32 v[56:57], v[60:61], v[56:57] op_sel_hi:[0,1]
	v_pk_fma_f32 v[56:57], v[48:49], v[48:49], v[56:57]
	v_mul_f32_e32 v60, v49, v49
	v_pk_add_f32 v[88:89], v[60:61], v[56:57] op_sel_hi:[0,1]
	s_waitcnt lgkmcnt(10)
	v_pk_mul_f32 v[56:57], v[194:195], v[108:109]
	s_nop 0
	v_pk_fma_f32 v[38:39], v[38:39], v[80:81], v[56:57] op_sel_hi:[1,0,1] neg_lo:[0,0,1] neg_hi:[0,0,1]
	v_pk_mul_f32 v[56:57], v[194:195], v[106:107]
	s_nop 0
	v_pk_fma_f32 v[36:37], v[36:37], v[80:81], v[56:57] op_sel_hi:[1,0,1] neg_lo:[0,0,1] neg_hi:[0,0,1]
	v_pk_mul_f32 v[56:57], v[194:195], v[104:105]
	s_nop 0
	v_pk_fma_f32 v[56:57], v[34:35], v[80:81], v[56:57] op_sel_hi:[1,0,1] neg_lo:[0,0,1] neg_hi:[0,0,1]
	v_pk_mul_f32 v[34:35], v[194:195], v[102:103]
	s_nop 0
	v_pk_fma_f32 v[60:61], v[32:33], v[80:81], v[34:35] op_sel_hi:[1,0,1] neg_lo:[0,0,1] neg_hi:[0,0,1]
	s_nop 0
	v_pk_fma_f32 v[32:33], v[60:61], v[60:61], v[88:89]
	v_mul_f32_e32 v34, v61, v61
	v_pk_add_f32 v[32:33], v[34:35], v[32:33] op_sel_hi:[0,1]
	v_pk_fma_f32 v[32:33], v[56:57], v[56:57], v[32:33]
	v_mul_f32_e32 v34, v57, v57
	v_pk_add_f32 v[32:33], v[34:35], v[32:33] op_sel_hi:[0,1]
	v_pk_fma_f32 v[32:33], v[36:37], v[36:37], v[32:33]
	v_mul_f32_e32 v34, v37, v37
	v_pk_add_f32 v[32:33], v[34:35], v[32:33] op_sel_hi:[0,1]
	v_pk_fma_f32 v[32:33], v[38:39], v[38:39], v[32:33]
	v_mul_f32_e32 v34, v39, v39
	v_pk_add_f32 v[88:89], v[34:35], v[32:33] op_sel_hi:[0,1]
	s_waitcnt lgkmcnt(8)
	v_pk_mul_f32 v[34:35], v[194:195], v[114:115]
	v_pk_mul_f32 v[32:33], v[194:195], v[116:117]
	v_pk_fma_f32 v[34:35], v[44:45], v[80:81], v[34:35] op_sel_hi:[1,0,1] neg_lo:[0,0,1] neg_hi:[0,0,1]
	v_pk_mul_f32 v[44:45], v[194:195], v[112:113]
	v_pk_fma_f32 v[32:33], v[46:47], v[80:81], v[32:33] op_sel_hi:[1,0,1] neg_lo:[0,0,1] neg_hi:[0,0,1]
	v_pk_fma_f32 v[42:43], v[42:43], v[80:81], v[44:45] op_sel_hi:[1,0,1] neg_lo:[0,0,1] neg_hi:[0,0,1]
	v_pk_mul_f32 v[44:45], v[194:195], v[110:111]
	s_nop 0
	v_pk_fma_f32 v[46:47], v[40:41], v[80:81], v[44:45] op_sel_hi:[1,0,1] neg_lo:[0,0,1] neg_hi:[0,0,1]
	s_nop 0
	v_pk_fma_f32 v[40:41], v[46:47], v[46:47], v[88:89]
	v_mul_f32_e32 v44, v47, v47
	v_pk_add_f32 v[40:41], v[44:45], v[40:41] op_sel_hi:[0,1]
	v_pk_fma_f32 v[40:41], v[42:43], v[42:43], v[40:41]
	v_mul_f32_e32 v44, v43, v43
	v_pk_add_f32 v[40:41], v[44:45], v[40:41] op_sel_hi:[0,1]
	v_pk_fma_f32 v[40:41], v[34:35], v[34:35], v[40:41]
	v_mul_f32_e32 v44, v35, v35
	v_pk_add_f32 v[40:41], v[44:45], v[40:41] op_sel_hi:[0,1]
	v_pk_fma_f32 v[40:41], v[32:33], v[32:33], v[40:41]
	v_mul_f32_e32 v44, v33, v33
	v_pk_add_f32 v[88:89], v[44:45], v[40:41] op_sel_hi:[0,1]
	s_waitcnt lgkmcnt(6)
	v_pk_mul_f32 v[40:41], v[194:195], v[124:125]
	s_nop 0
	v_pk_fma_f32 v[22:23], v[22:23], v[80:81], v[40:41] op_sel_hi:[1,0,1] neg_lo:[0,0,1] neg_hi:[0,0,1]
	v_pk_mul_f32 v[40:41], v[194:195], v[122:123]
	s_nop 0
	v_pk_fma_f32 v[20:21], v[20:21], v[80:81], v[40:41] op_sel_hi:[1,0,1] neg_lo:[0,0,1] neg_hi:[0,0,1]
	v_pk_mul_f32 v[40:41], v[194:195], v[120:121]
	s_nop 0
	v_pk_fma_f32 v[40:41], v[18:19], v[80:81], v[40:41] op_sel_hi:[1,0,1] neg_lo:[0,0,1] neg_hi:[0,0,1]
	v_pk_mul_f32 v[18:19], v[194:195], v[118:119]
	s_nop 0
	v_pk_fma_f32 v[44:45], v[16:17], v[80:81], v[18:19] op_sel_hi:[1,0,1] neg_lo:[0,0,1] neg_hi:[0,0,1]
	s_nop 0
	v_pk_fma_f32 v[16:17], v[44:45], v[44:45], v[88:89]
	v_mul_f32_e32 v18, v45, v45
	v_pk_add_f32 v[16:17], v[18:19], v[16:17] op_sel_hi:[0,1]
	v_pk_fma_f32 v[16:17], v[40:41], v[40:41], v[16:17]
	v_mul_f32_e32 v18, v41, v41
	v_pk_add_f32 v[16:17], v[18:19], v[16:17] op_sel_hi:[0,1]
	v_pk_fma_f32 v[16:17], v[20:21], v[20:21], v[16:17]
	v_mul_f32_e32 v18, v21, v21
	v_pk_add_f32 v[16:17], v[18:19], v[16:17] op_sel_hi:[0,1]
	v_pk_fma_f32 v[16:17], v[22:23], v[22:23], v[16:17]
	v_mul_f32_e32 v18, v23, v23
	v_pk_add_f32 v[88:89], v[18:19], v[16:17] op_sel_hi:[0,1]
	s_waitcnt lgkmcnt(4)
	v_pk_mul_f32 v[18:19], v[194:195], v[130:131]
	v_pk_mul_f32 v[16:17], v[194:195], v[132:133]
	v_pk_fma_f32 v[18:19], v[28:29], v[80:81], v[18:19] op_sel_hi:[1,0,1] neg_lo:[0,0,1] neg_hi:[0,0,1]
	v_pk_mul_f32 v[28:29], v[194:195], v[128:129]
	v_pk_fma_f32 v[16:17], v[30:31], v[80:81], v[16:17] op_sel_hi:[1,0,1] neg_lo:[0,0,1] neg_hi:[0,0,1]
	v_pk_fma_f32 v[26:27], v[26:27], v[80:81], v[28:29] op_sel_hi:[1,0,1] neg_lo:[0,0,1] neg_hi:[0,0,1]
	v_pk_mul_f32 v[28:29], v[194:195], v[126:127]
	s_nop 0
	v_pk_fma_f32 v[30:31], v[24:25], v[80:81], v[28:29] op_sel_hi:[1,0,1] neg_lo:[0,0,1] neg_hi:[0,0,1]
	s_nop 0
	v_pk_fma_f32 v[24:25], v[30:31], v[30:31], v[88:89]
	v_mul_f32_e32 v28, v31, v31
	v_pk_add_f32 v[24:25], v[28:29], v[24:25] op_sel_hi:[0,1]
	v_pk_fma_f32 v[24:25], v[26:27], v[26:27], v[24:25]
	v_mul_f32_e32 v28, v27, v27
	v_pk_add_f32 v[24:25], v[28:29], v[24:25] op_sel_hi:[0,1]
	v_pk_fma_f32 v[24:25], v[18:19], v[18:19], v[24:25]
	v_mul_f32_e32 v28, v19, v19
	v_pk_add_f32 v[24:25], v[28:29], v[24:25] op_sel_hi:[0,1]
	v_pk_fma_f32 v[24:25], v[16:17], v[16:17], v[24:25]
	v_mul_f32_e32 v28, v17, v17
	v_pk_add_f32 v[88:89], v[28:29], v[24:25] op_sel_hi:[0,1]
	s_waitcnt lgkmcnt(2)
	v_pk_mul_f32 v[24:25], v[194:195], v[140:141]
	s_nop 0
	v_pk_fma_f32 v[6:7], v[6:7], v[80:81], v[24:25] op_sel_hi:[1,0,1] neg_lo:[0,0,1] neg_hi:[0,0,1]
	v_pk_mul_f32 v[24:25], v[194:195], v[138:139]
	s_nop 0
	v_pk_fma_f32 v[4:5], v[4:5], v[80:81], v[24:25] op_sel_hi:[1,0,1] neg_lo:[0,0,1] neg_hi:[0,0,1]
	v_pk_mul_f32 v[24:25], v[194:195], v[136:137]
	s_nop 0
	v_pk_fma_f32 v[24:25], v[2:3], v[80:81], v[24:25] op_sel_hi:[1,0,1] neg_lo:[0,0,1] neg_hi:[0,0,1]
	v_pk_mul_f32 v[2:3], v[194:195], v[134:135]
	s_nop 0
	v_pk_fma_f32 v[28:29], v[0:1], v[80:81], v[2:3] op_sel_hi:[1,0,1] neg_lo:[0,0,1] neg_hi:[0,0,1]
	s_nop 0
	v_pk_fma_f32 v[0:1], v[28:29], v[28:29], v[88:89]
	v_mul_f32_e32 v2, v29, v29
	v_pk_add_f32 v[0:1], v[2:3], v[0:1] op_sel_hi:[0,1]
	v_pk_fma_f32 v[0:1], v[24:25], v[24:25], v[0:1]
	v_mul_f32_e32 v2, v25, v25
	v_pk_add_f32 v[0:1], v[2:3], v[0:1] op_sel_hi:[0,1]
	v_pk_fma_f32 v[0:1], v[4:5], v[4:5], v[0:1]
	v_mul_f32_e32 v2, v5, v5
	v_pk_add_f32 v[0:1], v[2:3], v[0:1] op_sel_hi:[0,1]
	v_pk_fma_f32 v[0:1], v[6:7], v[6:7], v[0:1]
	v_mul_f32_e32 v2, v7, v7
	v_pk_add_f32 v[88:89], v[2:3], v[0:1] op_sel_hi:[0,1]
	s_waitcnt lgkmcnt(0)
	v_pk_mul_f32 v[2:3], v[194:195], v[76:77]
	v_pk_mul_f32 v[0:1], v[194:195], v[78:79]
	v_pk_fma_f32 v[2:3], v[12:13], v[80:81], v[2:3] op_sel_hi:[1,0,1] neg_lo:[0,0,1] neg_hi:[0,0,1]
	v_pk_mul_f32 v[12:13], v[194:195], v[74:75]
	v_pk_fma_f32 v[0:1], v[14:15], v[80:81], v[0:1] op_sel_hi:[1,0,1] neg_lo:[0,0,1] neg_hi:[0,0,1]
	v_pk_fma_f32 v[10:11], v[10:11], v[80:81], v[12:13] op_sel_hi:[1,0,1] neg_lo:[0,0,1] neg_hi:[0,0,1]
	v_pk_mul_f32 v[12:13], v[194:195], v[72:73]
	s_nop 0
	v_pk_fma_f32 v[8:9], v[8:9], v[80:81], v[12:13] op_sel_hi:[1,0,1] neg_lo:[0,0,1] neg_hi:[0,0,1]
	s_nop 0
	v_pk_fma_f32 v[12:13], v[8:9], v[8:9], v[88:89]
	v_mul_f32_e32 v14, v9, v9
	v_pk_add_f32 v[12:13], v[14:15], v[12:13] op_sel_hi:[0,1]
	v_pk_fma_f32 v[12:13], v[10:11], v[10:11], v[12:13]
	v_mul_f32_e32 v14, v11, v11
	v_pk_add_f32 v[12:13], v[14:15], v[12:13] op_sel_hi:[0,1]
	v_pk_fma_f32 v[12:13], v[2:3], v[2:3], v[12:13]
	v_mul_f32_e32 v14, v3, v3
	v_pk_add_f32 v[12:13], v[14:15], v[12:13] op_sel_hi:[0,1]
	v_pk_fma_f32 v[12:13], v[0:1], v[0:1], v[12:13]
	v_mul_f32_e32 v14, v1, v1
	v_pk_add_f32 v[12:13], v[14:15], v[12:13] op_sel_hi:[0,1]
	v_mov_b32_e32 v13, v12
	s_nop 1
	v_permlane32_swap_b32_e32 v12, v13
	v_add_f32_e32 v12, v12, v13
	v_fmamk_f32 v12, v12, 0x3c000000, v205
	v_mul_f32_e32 v13, 0x4b800000, v12
	v_cmp_gt_f32_e32 vcc, s43, v12
	s_nop 1
	v_cndmask_b32_e32 v12, v12, v13, vcc
	v_rsq_f32_e32 v14, v12
	v_lshl_add_u64 v[12:13], v[82:83], 0, s[8:9]
	v_lshl_add_u64 v[12:13], v[12:13], 0, v[214:215]
	v_mul_f32_e32 v15, 0x45800000, v14
	v_cndmask_b32_e32 v14, v14, v15, vcc
	v_mul_f32_e32 v14, 0x3f24fd5c, v14
	v_pk_mul_f32 v[72:73], v[86:87], v[14:15] op_sel_hi:[1,0]
	v_pk_mul_f32 v[52:53], v[52:53], v[14:15] op_sel_hi:[1,0]
	s_waitcnt vmcnt(0)
	v_pk_mul_f32 v[68:69], v[144:145], v[72:73]
	v_pk_mul_f32 v[72:73], v[84:85], v[14:15] op_sel_hi:[1,0]
	v_pk_mul_f32 v[52:53], v[148:149], v[52:53]
	v_pk_mul_f32 v[70:71], v[146:147], v[72:73]
	v_cvt_pk_bf16_f32 v68, v68, v69
	v_cvt_pk_bf16_f32 v69, v70, v71
	v_cvt_pk_bf16_f32 v70, v52, v53
	v_pk_mul_f32 v[52:53], v[54:55], v[14:15] op_sel_hi:[1,0]
	s_nop 0
	v_permlane32_swap_b32_e32 v68, v70
	v_pk_mul_f32 v[52:53], v[150:151], v[52:53]
	v_pk_mul_f32 v[62:63], v[62:63], v[14:15] op_sel_hi:[1,0]
	v_cvt_pk_bf16_f32 v71, v52, v53
	s_nop 1
	v_permlane32_swap_b32_e32 v69, v71
	global_store_dwordx4 v[12:13], v[68:71], off
	v_pk_mul_f32 v[58:59], v[58:59], v[14:15] op_sel_hi:[1,0]
	v_pk_mul_f32 v[50:51], v[50:51], v[14:15] op_sel_hi:[1,0]
	v_pk_mul_f32 v[48:49], v[48:49], v[14:15] op_sel_hi:[1,0]
	v_pk_mul_f32 v[56:57], v[56:57], v[14:15] op_sel_hi:[1,0]
	v_pk_mul_f32 v[36:37], v[36:37], v[14:15] op_sel_hi:[1,0]
	v_pk_mul_f32 v[38:39], v[38:39], v[14:15] op_sel_hi:[1,0]
	v_pk_mul_f32 v[46:47], v[46:47], v[14:15] op_sel_hi:[1,0]
	v_pk_mul_f32 v[42:43], v[42:43], v[14:15] op_sel_hi:[1,0]
	v_pk_mul_f32 v[34:35], v[34:35], v[14:15] op_sel_hi:[1,0]
	v_pk_mul_f32 v[32:33], v[32:33], v[14:15] op_sel_hi:[1,0]
	v_pk_mul_f32 v[40:41], v[40:41], v[14:15] op_sel_hi:[1,0]
	v_pk_mul_f32 v[20:21], v[20:21], v[14:15] op_sel_hi:[1,0]
	v_pk_mul_f32 v[22:23], v[22:23], v[14:15] op_sel_hi:[1,0]
	v_pk_mul_f32 v[30:31], v[30:31], v[14:15] op_sel_hi:[1,0]
	v_pk_mul_f32 v[26:27], v[26:27], v[14:15] op_sel_hi:[1,0]
	v_pk_mul_f32 v[18:19], v[18:19], v[14:15] op_sel_hi:[1,0]
	v_pk_mul_f32 v[16:17], v[16:17], v[14:15] op_sel_hi:[1,0]
	v_pk_mul_f32 v[24:25], v[24:25], v[14:15] op_sel_hi:[1,0]
	v_pk_mul_f32 v[4:5], v[4:5], v[14:15] op_sel_hi:[1,0]
	v_pk_mul_f32 v[6:7], v[6:7], v[14:15] op_sel_hi:[1,0]
	v_pk_mul_f32 v[8:9], v[8:9], v[14:15] op_sel_hi:[1,0]
	v_pk_mul_f32 v[10:11], v[10:11], v[14:15] op_sel_hi:[1,0]
	v_pk_mul_f32 v[2:3], v[2:3], v[14:15] op_sel_hi:[1,0]
	v_pk_mul_f32 v[0:1], v[0:1], v[14:15] op_sel_hi:[1,0]
	v_pk_mul_f32 v[52:53], v[152:153], v[62:63]
	v_pk_mul_f32 v[54:55], v[154:155], v[58:59]
	v_pk_mul_f32 v[50:51], v[156:157], v[50:51]
	v_pk_mul_f32 v[48:49], v[158:159], v[48:49]
	v_cvt_pk_bf16_f32 v52, v52, v53
	v_cvt_pk_bf16_f32 v53, v54, v55
	v_cvt_pk_bf16_f32 v54, v50, v51
	v_cvt_pk_bf16_f32 v55, v48, v49
	s_nop 0
	v_permlane32_swap_b32_e32 v52, v54
	v_permlane32_swap_b32_e32 v53, v55
	global_store_dwordx4 v[12:13], v[52:55], off offset:32
	s_nop 0
	v_pk_mul_f32 v[58:59], v[60:61], v[14:15] op_sel_hi:[1,0]
	v_pk_mul_f32 v[50:51], v[162:163], v[56:57]
	v_pk_mul_f32 v[48:49], v[160:161], v[58:59]
	v_pk_mul_f32 v[52:53], v[36:37], v[164:165]
	v_pk_mul_f32 v[54:55], v[38:39], v[166:167]
	v_cvt_pk_bf16_f32 v36, v48, v49
	v_cvt_pk_bf16_f32 v37, v50, v51
	v_cvt_pk_bf16_f32 v38, v52, v53
	v_cvt_pk_bf16_f32 v39, v54, v55
	s_nop 0
	v_permlane32_swap_b32_e32 v36, v38
	v_permlane32_swap_b32_e32 v37, v39
	global_store_dwordx4 v[12:13], v[36:39], off offset:64
	s_nop 1
	s_nop 0
	v_pk_mul_f32 v[36:37], v[46:47], v[168:169]
	v_pk_mul_f32 v[38:39], v[42:43], v[170:171]
	v_pk_mul_f32 v[34:35], v[34:35], v[172:173]
	v_pk_mul_f32 v[42:43], v[32:33], v[174:175]
	v_cvt_pk_bf16_f32 v32, v36, v37
	v_cvt_pk_bf16_f32 v33, v38, v39
	v_cvt_pk_bf16_f32 v34, v34, v35
	v_cvt_pk_bf16_f32 v35, v42, v43
	s_nop 0
	v_permlane32_swap_b32_e32 v32, v34
	v_permlane32_swap_b32_e32 v33, v35
	global_store_dwordx4 v[12:13], v[32:35], off offset:96
	s_nop 0
	v_pk_mul_f32 v[42:43], v[44:45], v[14:15] op_sel_hi:[1,0]
	v_pk_mul_f32 v[34:35], v[40:41], v[178:179]
	v_pk_mul_f32 v[32:33], v[42:43], v[176:177]
	v_pk_mul_f32 v[36:37], v[20:21], v[180:181]
	v_pk_mul_f32 v[38:39], v[22:23], v[182:183]
	v_cvt_pk_bf16_f32 v20, v32, v33
	v_cvt_pk_bf16_f32 v21, v34, v35
	v_cvt_pk_bf16_f32 v22, v36, v37
	v_cvt_pk_bf16_f32 v23, v38, v39
	s_nop 0
	v_permlane32_swap_b32_e32 v20, v22
	v_permlane32_swap_b32_e32 v21, v23
	global_store_dwordx4 v[12:13], v[20:23], off offset:128
	s_nop 1
	s_nop 0
	v_pk_mul_f32 v[20:21], v[30:31], v[184:185]
	v_pk_mul_f32 v[22:23], v[26:27], v[186:187]
	v_pk_mul_f32 v[18:19], v[18:19], v[188:189]
	v_pk_mul_f32 v[26:27], v[16:17], v[190:191]
	v_cvt_pk_bf16_f32 v16, v20, v21
	v_cvt_pk_bf16_f32 v17, v22, v23
	v_cvt_pk_bf16_f32 v18, v18, v19
	v_cvt_pk_bf16_f32 v19, v26, v27
	s_nop 0
	v_permlane32_swap_b32_e32 v16, v18
	v_permlane32_swap_b32_e32 v17, v19
	global_store_dwordx4 v[12:13], v[16:19], off offset:160
	s_nop 0
	v_pk_mul_f32 v[26:27], v[28:29], v[14:15] op_sel_hi:[1,0]
	v_pk_mul_f32 v[18:19], v[24:25], v[226:227]
	v_pk_mul_f32 v[16:17], v[26:27], v[224:225]
	v_pk_mul_f32 v[20:21], v[4:5], v[228:229]
	v_pk_mul_f32 v[22:23], v[6:7], v[230:231]
	v_cvt_pk_bf16_f32 v4, v16, v17
	v_cvt_pk_bf16_f32 v5, v18, v19
	v_cvt_pk_bf16_f32 v6, v20, v21
	v_cvt_pk_bf16_f32 v7, v22, v23
	s_nop 0
	v_permlane32_swap_b32_e32 v4, v6
	v_permlane32_swap_b32_e32 v5, v7
	global_store_dwordx4 v[12:13], v[4:7], off offset:192
	s_nop 1
	s_nop 0
	v_pk_mul_f32 v[4:5], v[8:9], v[244:245]
	v_pk_mul_f32 v[6:7], v[10:11], v[246:247]
	v_pk_mul_f32 v[2:3], v[2:3], v[248:249]
	v_pk_mul_f32 v[8:9], v[0:1], v[250:251]
	v_cvt_pk_bf16_f32 v0, v4, v5
	v_cvt_pk_bf16_f32 v1, v6, v7
	v_cvt_pk_bf16_f32 v2, v2, v3
	v_cvt_pk_bf16_f32 v3, v8, v9
	s_nop 0
	v_permlane32_swap_b32_e32 v0, v2
	v_permlane32_swap_b32_e32 v1, v3
	global_store_dwordx4 v[12:13], v[0:3], off offset:224
	s_branch .LBB0_2798
